# v26 + MoE epilogues: the four token-index loads of a tile are issued before its k-loop instead of at the epilogue entry (one dependent round trip less per tile)
# speedup vs baseline: 1.0025x; 1.0025x over previous
.LBB0_703:
	s_movk_i32 s0, 0xab
	v_mul_lo_u32 v69, v134, s0
	v_bfe_u32 v69, v69, 10, 6
	v_mul_lo_u32 v70, v69, -6
	v_add_u32_e32 v70, v70, v134
	v_cmp_gt_i32_e32 vcc, 5, v70
	v_min_i32_e32 v77, 4, v70
	s_and_b32 s0, s83, 7
	v_cndmask_b32_e64 v71, 2, 1, vcc
	v_add_u32_e32 v76, 1, v70
	v_add_u32_e32 v77, -1, v77
	v_cmp_gt_i32_e32 vcc, 3, v70
	s_cmp_lt_u32 s0, 4
	v_lshlrev_b32_e32 v69, 2, v69
	v_cndmask_b32_e64 v70, v71, 0, vcc
	v_cndmask_b32_e32 v71, v77, v76, vcc
	s_cselect_b64 vcc, -1, 0
	s_lshl_b32 s0, s83, 7
	v_or_b32_e32 v70, v70, v69
	v_add_u32_e32 v69, v71, v69
	s_and_b32 s0, s0, 0x180
	s_waitcnt vmcnt(3)
	v_lshlrev_b32_e32 v135, 10, v64
	s_waitcnt vmcnt(2)
	v_lshlrev_b32_e32 v153, 10, v65
	v_cndmask_b32_e32 v64, v69, v70, vcc
	v_add_lshl_u32 v65, s0, v144, 10
	v_lshl_add_u32 v156, v64, 19, v65
	v_lshlrev_b32_e32 v64, 1, v133
	v_bfe_u32 v138, v66, 6, 1
	v_and_b32_e32 v65, 15, v66
	v_bfe_u32 v140, v66, 4, 2
	v_lshl_add_u32 v141, v75, 1, v64
	v_lshl_add_u32 v158, v72, 1, v64
	v_lshl_add_u32 v159, v73, 1, v64
	v_lshl_add_u32 v160, v74, 1, v64
	v_ashrrev_i32_e32 v64, 1, v66
	s_movk_i32 s0, 0xffc0
	v_and_or_b32 v157, v64, s0, v65
	v_lshlrev_b32_e32 v64, 4, v140
	v_lshl_or_b32 v65, v138, 6, v65
	s_movk_i32 s0, 0xa0
	v_mad_u64_u32 v[136:137], s[0:1], v157, s0, v[64:65]
	v_mul_u32_u24_e32 v65, 0x50, v65
	v_lshlrev_b32_e32 v65, 1, v65
	s_waitcnt vmcnt(1)
	v_lshlrev_b32_e32 v154, 10, v67
	s_waitcnt vmcnt(0)
	v_lshlrev_b32_e32 v155, 10, v68
	v_or_b32_e32 v67, 0x3c0, v133
	v_add_u32_e32 v137, v64, v65
	v_or_b32_e32 v66, 0xf000, v64
	v_add_u32_e32 v68, 0x1400, v65
	v_add_u32_e32 v65, 0x1e00, v65
	v_or_b32_e32 v64, 0xf040, v64
	v_add_u32_e32 v163, v64, v68
	v_add_u32_e32 v164, v64, v65
	v_add_u32_e32 v166, v67, v149
	v_mov_b32_e32 v64, 0
	s_mov_b32 s2, 0
	v_add_u32_e32 v161, v66, v68
	v_add_u32_e32 v162, v66, v65
	v_add_u32_e32 v165, v67, v148
	v_add_u32_e32 v167, v67, v147
	v_add_u32_e32 v168, 0x8000, v166
	v_add_u32_e32 v169, v67, v146
	v_add_u32_e32 v170, 0x10000, v166
	v_add_u32_e32 v171, v67, v145
	v_add_u32_e32 v172, 0x18000, v166
	v_mov_b32_e32 v173, v148
	v_mov_b32_e32 v174, v149
	v_mov_b32_e32 v175, v147
	v_mov_b32_e32 v176, v146
	v_mov_b32_e32 v177, v145
	v_mov_b32_e32 v178, v135
	v_mov_b32_e32 v179, v156
	v_mov_b32_e32 v180, v153
	v_mov_b32_e32 v181, v154
	v_mov_b32_e32 v182, v155
	v_mov_b32_e32 v65, v64
	v_mov_b32_e32 v66, v64
	v_mov_b32_e32 v67, v64
	v_mov_b32_e32 v80, v64
	v_mov_b32_e32 v81, v64
	v_mov_b32_e32 v82, v64
	v_mov_b32_e32 v83, v64
	v_mov_b32_e32 v96, v64
	v_mov_b32_e32 v97, v64
	v_mov_b32_e32 v98, v64
	v_mov_b32_e32 v99, v64
	v_mov_b32_e32 v112, v64
	v_mov_b32_e32 v113, v64
	v_mov_b32_e32 v114, v64
	v_mov_b32_e32 v115, v64
	v_mov_b32_e32 v72, v64
	v_mov_b32_e32 v73, v64
	v_mov_b32_e32 v74, v64
	v_mov_b32_e32 v75, v64
	v_mov_b32_e32 v88, v64
	v_mov_b32_e32 v89, v64
	v_mov_b32_e32 v90, v64
	v_mov_b32_e32 v91, v64
	v_mov_b32_e32 v104, v64
	v_mov_b32_e32 v105, v64
	v_mov_b32_e32 v106, v64
	v_mov_b32_e32 v107, v64
	v_mov_b32_e32 v120, v64
	v_mov_b32_e32 v121, v64
	v_mov_b32_e32 v122, v64
	v_mov_b32_e32 v123, v64
	v_mov_b32_e32 v68, v64
	v_mov_b32_e32 v69, v64
	v_mov_b32_e32 v70, v64
	v_mov_b32_e32 v71, v64
	v_mov_b32_e32 v84, v64
	v_mov_b32_e32 v85, v64
	v_mov_b32_e32 v86, v64
	v_mov_b32_e32 v87, v64
	v_mov_b32_e32 v100, v64
	v_mov_b32_e32 v101, v64
	v_mov_b32_e32 v102, v64
	v_mov_b32_e32 v103, v64
	v_mov_b32_e32 v116, v64
	v_mov_b32_e32 v117, v64
	v_mov_b32_e32 v118, v64
	v_mov_b32_e32 v119, v64
	v_mov_b32_e32 v76, v64
	v_mov_b32_e32 v77, v64
	v_mov_b32_e32 v78, v64
	v_mov_b32_e32 v79, v64
	v_mov_b32_e32 v92, v64
	v_mov_b32_e32 v93, v64
	v_mov_b32_e32 v94, v64
	v_mov_b32_e32 v95, v64
	v_mov_b32_e32 v108, v64
	v_mov_b32_e32 v109, v64
	v_mov_b32_e32 v110, v64
	v_mov_b32_e32 v111, v64
	v_mov_b32_e32 v124, v64
	v_mov_b32_e32 v125, v64
	v_mov_b32_e32 v126, v64
	v_mov_b32_e32 v127, v64
	v_add_u32_e32 v252, -1, v142
	v_add_u32_e32 v244, v139, v157
	v_add3_u32 v246, v139, v157, 16
	v_add3_u32 v248, v139, v157, 32
	v_add3_u32 v250, v139, v157, 48
	v_readlane_b32 s100, v237, 42
	v_readlane_b32 s101, v237, 43
	v_min_i32_e32 v244, v244, v252
	v_min_i32_e32 v246, v246, v252
	v_min_i32_e32 v248, v248, v252
	v_min_i32_e32 v250, v250, v252
	v_mov_b32_e32 v245, 0
	v_mov_b32_e32 v247, 0
	v_mov_b32_e32 v249, 0
	v_mov_b32_e32 v251, 0
	v_mov_b32_e32 v254, v132
	v_mov_b32_e32 v255, 0
	v_lshlrev_b64 v[254:255], 17, v[254:255]
	v_lshl_add_u64 v[254:255], s[100:101], 0, v[254:255]
	v_lshl_add_u64 v[244:245], v[244:245], 2, v[254:255]
	v_lshl_add_u64 v[246:247], v[246:247], 2, v[254:255]
	v_lshl_add_u64 v[248:249], v[248:249], 2, v[254:255]
	v_lshl_add_u64 v[250:251], v[250:251], 2, v[254:255]
	global_load_dword v240, v[244:245], off
	global_load_dword v241, v[246:247], off
	global_load_dword v242, v[248:249], off
	global_load_dword v243, v[250:251], off
	s_branch .LBB0_705

.LBB0_723:
	v_readlane_b32 s100, v237, 44
	v_readlane_b32 s101, v237, 45
	s_and_b32 s98, s82, 4
	s_mov_b32 s99, 0
	s_waitcnt vmcnt(0)
	v_mov_b32_e32 v244, v240
	v_mov_b32_e32 v245, 0
	v_mov_b32_e32 v246, v241
	v_mov_b32_e32 v247, 0
	v_mov_b32_e32 v248, v242
	v_mov_b32_e32 v249, 0
	v_mov_b32_e32 v250, v243
	v_mov_b32_e32 v251, 0
	v_lshl_add_u64 v[244:245], v[244:245], 3, s[100:101]
	v_lshl_add_u64 v[246:247], v[246:247], 3, s[100:101]
	v_lshl_add_u64 v[248:249], v[248:249], 3, s[100:101]
	v_lshl_add_u64 v[250:251], v[250:251], 3, s[100:101]
	v_lshl_add_u64 v[244:245], v[244:245], 0, s[98:99]
	v_lshl_add_u64 v[246:247], v[246:247], 0, s[98:99]
	v_lshl_add_u64 v[248:249], v[248:249], 0, s[98:99]
	v_lshl_add_u64 v[250:251], v[250:251], 0, s[98:99]
	global_load_dword v252, v[244:245], off
	global_load_dword v253, v[246:247], off
	global_load_dword v254, v[248:249], off
	global_load_dword v255, v[250:251], off
	s_lshl_b32 s0, s82, 1
	v_and_or_b32 v130, s0, 6, v138
	v_lshlrev_b32_e32 v130, 5, v130
	v_lshlrev_b32_e32 v133, 2, v140
	v_add_u32_e32 v140, v157, v139
	s_and_b32 s6, s82, 7
	v_cmp_lt_i32_e32 vcc, v140, v142
	v_lshlrev_b32_e32 v130, 1, v130
	v_lshlrev_b32_e32 v136, 1, v133
	s_and_saveexec_b64 s[0:1], vcc
	s_cbranch_execz .LBB0_725
	v_mov_b32_e32 v133, v131
	v_readlane_b32 s4, v237, 42
	v_lshlrev_b64 v[158:159], 17, v[132:133]
	v_readlane_b32 s5, v237, 43
	v_ashrrev_i32_e32 v141, 31, v140
	s_and_b32 s2, s6, 4
	v_lshl_add_u64 v[158:159], s[4:5], 0, v[158:159]
	v_lshl_add_u64 v[158:159], v[140:141], 2, v[158:159]
	v_readlane_b32 s4, v237, 44
	v_readlane_b32 s5, v237, 45
	v_mul_f32_e32 v133, 0xbfb8aa3b, v124
	v_exp_f32_e32 v133, v133
	v_mov_b32_e32 v137, v131
	v_add_f32_e32 v133, 1.0, v133
	v_ashrrev_i32_e32 v159, 31, v158
	v_lshl_add_u64 v[158:159], v[158:159], 3, s[4:5]
	v_lshl_add_u64 v[158:159], v[158:159], 0, s[2:3]
	v_rcp_f32_e32 v158, v133
	v_mul_f32_e32 v133, 0xbfb8aa3b, v125
	v_exp_f32_e32 v133, v133
	s_lshl_b32 s2, s6, 7
	s_and_b32 s2, s2, 0x200
	v_add_f32_e32 v133, 1.0, v133
	v_rcp_f32_e32 v159, v133
	s_nop 0
	v_pk_mul_f32 v[124:125], v[124:125], v[158:159]
	s_nop 0
	v_pk_mul_f32 v[120:121], v[124:125], v[120:121]
	v_mul_f32_e32 v124, 0xbfb8aa3b, v126
	v_mul_f32_e32 v125, 0xbfb8aa3b, v127
	v_exp_f32_e32 v124, v124
	v_exp_f32_e32 v125, v125
	v_add_f32_e32 v124, 1.0, v124
	v_add_f32_e32 v125, 1.0, v125
	v_rcp_f32_e32 v124, v124
	v_rcp_f32_e32 v125, v125
	s_waitcnt vmcnt(0)
	v_mov_b32_e32 v138, v252
	v_pk_mul_f32 v[120:121], v[120:121], v[138:139] op_sel_hi:[1,0]
	v_pk_mul_f32 v[124:125], v[126:127], v[124:125]
	v_cvt_pk_bf16_f32 v120, v120, v121
	v_pk_mul_f32 v[122:123], v[124:125], v[122:123]
	s_nop 0
	v_pk_mul_f32 v[122:123], v[122:123], v[138:139] op_sel_hi:[1,0]
	s_nop 0
	v_cvt_pk_bf16_f32 v121, v122, v123
	v_add_u32_e32 v122, v140, v143
	v_ashrrev_i32_e32 v123, 31, v122
	v_lshlrev_b64 v[122:123], 10, v[122:123]
	v_lshl_add_u64 v[122:123], s[88:89], 0, v[122:123]
	v_lshl_add_u64 v[122:123], v[122:123], 0, s[2:3]
	v_lshl_add_u64 v[122:123], v[122:123], 0, v[130:131]
	v_lshl_add_u64 v[122:123], v[122:123], 0, v[136:137]
	global_store_dwordx2 v[122:123], v[120:121], off
	v_mul_f32_e32 v120, 0xbfb8aa3b, v116
	v_mul_f32_e32 v121, 0xbfb8aa3b, v117
	v_exp_f32_e32 v120, v120
	v_exp_f32_e32 v121, v121
	v_add_f32_e32 v120, 1.0, v120
	v_add_f32_e32 v121, 1.0, v121
	v_rcp_f32_e32 v120, v120
	v_rcp_f32_e32 v121, v121
	s_nop 0
	v_pk_mul_f32 v[116:117], v[116:117], v[120:121]
	s_nop 0
	v_pk_mul_f32 v[112:113], v[116:117], v[112:113]
	v_mul_f32_e32 v116, 0xbfb8aa3b, v118
	v_mul_f32_e32 v117, 0xbfb8aa3b, v119
	v_exp_f32_e32 v116, v116
	v_exp_f32_e32 v117, v117
	v_pk_mul_f32 v[112:113], v[112:113], v[138:139] op_sel_hi:[1,0]
	v_add_f32_e32 v116, 1.0, v116
	v_add_f32_e32 v117, 1.0, v117
	v_rcp_f32_e32 v116, v116
	v_rcp_f32_e32 v117, v117
	v_cvt_pk_bf16_f32 v112, v112, v113
	v_pk_mul_f32 v[116:117], v[118:119], v[116:117]
	s_nop 0
	v_pk_mul_f32 v[114:115], v[116:117], v[114:115]
	s_nop 0
	v_pk_mul_f32 v[114:115], v[114:115], v[138:139] op_sel_hi:[1,0]
	s_nop 0
	v_cvt_pk_bf16_f32 v113, v114, v115
	global_store_dwordx2 v[122:123], v[112:113], off offset:32

.LBB0_843:
	v_lshlrev_b32_e32 v65, 1, v136
	v_lshl_add_u32 v155, v74, 1, v65
	v_lshl_add_u32 v156, v71, 1, v65
	v_lshl_add_u32 v157, v72, 1, v65
	v_lshl_add_u32 v158, v73, 1, v65
	v_or_b32_e32 v65, 0xc0, v136
	s_waitcnt lgkmcnt(0)
	s_barrier
	s_waitcnt vmcnt(15)
	ds_write_b128 v155, v[0:3] offset:40960
	s_waitcnt vmcnt(14)
	ds_write_b128 v155, v[8:11] offset:61440
	s_waitcnt vmcnt(13)
	ds_write_b128 v156, v[16:19] offset:40960
	s_waitcnt vmcnt(12)
	ds_write_b128 v156, v[24:27] offset:61440
	s_waitcnt vmcnt(11)
	ds_write_b128 v157, v[28:31] offset:40960
	s_waitcnt vmcnt(10)
	ds_write_b128 v157, v[36:39] offset:61440
	s_waitcnt vmcnt(9)
	ds_write_b128 v158, v[44:47] offset:40960
	s_waitcnt vmcnt(8)
	ds_write_b128 v158, v[56:59] offset:61440
	v_add_u32_e32 v44, v65, v142
	v_mov_b32_e32 v132, v44
	v_mul_lo_u32 v66, v146, s6
	v_lshl_add_u64 v[0:1], v[132:133], 1, s[88:89]
	v_add_u32_e32 v132, v65, v144
	global_load_dwordx4 v[0:3], v[0:1], off
	v_bfe_u32 v66, v66, 10, 6
	v_lshl_add_u64 v[8:9], v[132:133], 1, s[18:19]
	v_add_u32_e32 v132, 0x4000, v44
	global_load_dwordx4 v[8:11], v[8:9], off
	v_mul_lo_u32 v67, v66, -6
	v_lshl_add_u64 v[16:17], v[132:133], 1, s[88:89]
	v_add_u32_e32 v132, v65, v137
	global_load_dwordx4 v[16:19], v[16:17], off
	v_add_u32_e32 v151, v67, v146
	v_lshl_add_u64 v[24:25], v[132:133], 1, s[18:19]
	v_add_u32_e32 v132, 0x8000, v44
	global_load_dwordx4 v[24:27], v[24:25], off
	v_cmp_gt_i32_e32 vcc, 5, v151
	v_lshl_add_u64 v[28:29], v[132:133], 1, s[88:89]
	v_add_u32_e32 v132, v65, v148
	global_load_dwordx4 v[28:31], v[28:29], off
	v_cndmask_b32_e64 v67, 2, 1, vcc
	v_lshl_add_u64 v[36:37], v[132:133], 1, s[18:19]
	v_add_u32_e32 v132, 0xc000, v44
	global_load_dwordx4 v[36:39], v[36:37], off
	v_cmp_gt_i32_e64 s[12:13], 3, v151
	v_lshl_add_u64 v[44:45], v[132:133], 1, s[88:89]
	v_add_u32_e32 v132, v65, v149
	global_load_dwordx4 v[44:47], v[44:45], off
	v_cndmask_b32_e64 v152, v67, 0, s[12:13]
	v_lshl_add_u64 v[56:57], v[132:133], 1, s[18:19]
	global_load_dwordx4 v[56:59], v[56:57], off
	v_add_u32_e32 v64, v64, v145
	v_add_lshl_u32 v150, v64, v140, 9
	s_lshl_b32 s0, s33, 15
	v_lshlrev_b32_e32 v64, 20, v66
	v_lshlrev_b32_e32 v66, 18, v152
	s_and_b32 s0, s0, 0x38000
	v_or_b32_e32 v64, v66, v64
	v_or_b32_e32 v64, s0, v64
	v_add_u32_e32 v153, v64, v141
	v_and_b32_e32 v64, 15, v131
	v_bfe_u32 v159, v131, 4, 2
	v_ashrrev_i32_e32 v66, 1, v131
	s_movk_i32 s0, 0xffc0
	v_and_or_b32 v154, v66, s0, v64
	v_lshlrev_b32_e32 v64, 4, v159
	v_and_b32_e32 v66, 0x4f, v131
	s_movk_i32 s0, 0xa0
	v_mad_u64_u32 v[134:135], s[0:1], v154, s0, v[64:65]
	v_mul_u32_u24_e32 v66, 0x50, v66
	v_lshl_add_u32 v135, v66, 1, v64
	v_add_u32_e32 v64, v144, v143
	v_add_u32_e32 v164, v65, v64
	v_add_u32_e32 v166, v136, v64
	ds_read_b128 v[64:67], v134
	ds_read_b128 v[68:71], v134 offset:2560
	ds_read_b128 v[72:75], v135 offset:20480
	ds_read_b128 v[76:79], v135 offset:23040
	ds_read_b128 v[80:83], v134 offset:5120
	ds_read_b128 v[84:87], v134 offset:7680
	ds_read_b128 v[88:91], v135 offset:25600
	ds_read_b128 v[92:95], v135 offset:28160
	v_add_u32_e32 v162, v142, v136
	s_mov_b32 s2, 2
	s_mov_b32 s14, 0
	v_add_u32_e32 v160, 0xf000, v135
	v_add_u32_e32 v161, 0xf040, v135
	v_add_u32_e32 v163, 0x1c0, v162
	v_add_u32_e32 v165, 0x41c0, v162
	v_add_u32_e32 v167, 0x20c0, v166
	v_add_u32_e32 v168, 0x81c0, v162
	v_add_u32_e32 v169, 0x40c0, v166
	v_add_u32_e32 v170, 0xc1c0, v162
	v_add_u32_e32 v171, 0x60c0, v166
	v_add_u32_e32 v172, 0x2000, v153
	v_add_u32_e32 v173, 0x4000, v153
	v_add_u32_e32 v174, 0x6000, v153
	s_setprio 1
	s_waitcnt lgkmcnt(5)
	v_mfma_f32_16x16x32_bf16 v[96:99], v[72:75], v[64:67], 0
	v_mfma_f32_16x16x32_bf16 v[100:103], v[72:75], v[68:71], 0
	s_waitcnt lgkmcnt(3)
	v_mfma_f32_16x16x32_bf16 v[104:107], v[72:75], v[80:83], 0
	s_waitcnt lgkmcnt(2)
	v_mfma_f32_16x16x32_bf16 v[72:75], v[72:75], v[84:87], 0
	v_mfma_f32_16x16x32_bf16 v[108:111], v[76:79], v[64:67], 0
	v_mfma_f32_16x16x32_bf16 v[112:115], v[76:79], v[68:71], 0
	v_mfma_f32_16x16x32_bf16 v[116:119], v[76:79], v[80:83], 0
	v_mfma_f32_16x16x32_bf16 v[76:79], v[76:79], v[84:87], 0
	s_waitcnt lgkmcnt(1)
	v_mfma_f32_16x16x32_bf16 v[120:123], v[88:91], v[64:67], 0
	v_mfma_f32_16x16x32_bf16 v[124:127], v[88:91], v[68:71], 0
	v_mfma_f32_16x16x32_bf16 v[176:179], v[88:91], v[80:83], 0
	v_mfma_f32_16x16x32_bf16 v[88:91], v[88:91], v[84:87], 0
	s_waitcnt lgkmcnt(0)
	v_mfma_f32_16x16x32_bf16 v[64:67], v[92:95], v[64:67], 0
	v_mfma_f32_16x16x32_bf16 v[68:71], v[92:95], v[68:71], 0
	v_mfma_f32_16x16x32_bf16 v[80:83], v[92:95], v[80:83], 0
	v_mfma_f32_16x16x32_bf16 v[84:87], v[92:95], v[84:87], 0
	s_setprio 0
	ds_read_b128 v[92:95], v134 offset:64
	ds_read_b128 v[180:183], v134 offset:2624
	ds_read_b128 v[184:187], v135 offset:20544
	ds_read_b128 v[188:191], v135 offset:23104
	ds_read_b128 v[192:195], v134 offset:5184
	ds_read_b128 v[196:199], v134 offset:7744
	ds_read_b128 v[200:203], v135 offset:25664
	ds_read_b128 v[204:207], v135 offset:28224
	s_setprio 1
	s_waitcnt lgkmcnt(5)
	v_mfma_f32_16x16x32_bf16 v[96:99], v[184:187], v[92:95], v[96:99]
	v_mfma_f32_16x16x32_bf16 v[100:103], v[184:187], v[180:183], v[100:103]
	s_waitcnt lgkmcnt(3)
	v_mfma_f32_16x16x32_bf16 v[104:107], v[184:187], v[192:195], v[104:107]
	s_waitcnt lgkmcnt(2)
	v_mfma_f32_16x16x32_bf16 v[72:75], v[184:187], v[196:199], v[72:75]
	v_mfma_f32_16x16x32_bf16 v[108:111], v[188:191], v[92:95], v[108:111]
	v_mfma_f32_16x16x32_bf16 v[112:115], v[188:191], v[180:183], v[112:115]
	v_mfma_f32_16x16x32_bf16 v[116:119], v[188:191], v[192:195], v[116:119]
	v_mfma_f32_16x16x32_bf16 v[76:79], v[188:191], v[196:199], v[76:79]
	s_waitcnt lgkmcnt(1)
	v_mfma_f32_16x16x32_bf16 v[120:123], v[200:203], v[92:95], v[120:123]
	v_mfma_f32_16x16x32_bf16 v[124:127], v[200:203], v[180:183], v[124:127]
	v_mfma_f32_16x16x32_bf16 v[88:91], v[200:203], v[196:199], v[88:91]
	s_waitcnt lgkmcnt(0)
	v_mfma_f32_16x16x32_bf16 v[64:67], v[204:207], v[92:95], v[64:67]
	v_mfma_f32_16x16x32_bf16 v[68:71], v[204:207], v[180:183], v[68:71]
	v_mfma_f32_16x16x32_bf16 v[80:83], v[204:207], v[192:195], v[80:83]
	v_mfma_f32_16x16x32_bf16 v[84:87], v[204:207], v[196:199], v[84:87]
	v_mfma_f32_16x16x32_bf16 v[176:179], v[200:203], v[192:195], v[176:179]
	s_setprio 0
	v_add_u32_e32 v132, 0x100, v162
	s_barrier
	s_waitcnt vmcnt(15)
	ds_write_b128 v155, v[4:7]
	s_waitcnt vmcnt(14)
	ds_write_b128 v155, v[12:15] offset:20480
	s_waitcnt vmcnt(13)
	ds_write_b128 v156, v[20:23]
	s_waitcnt vmcnt(12)
	ds_write_b128 v156, v[32:35] offset:20480
	s_waitcnt vmcnt(11)
	ds_write_b128 v157, v[40:43]
	s_waitcnt vmcnt(10)
	ds_write_b128 v157, v[48:51] offset:20480
	s_waitcnt vmcnt(9)
	ds_write_b128 v158, v[52:55]
	s_waitcnt vmcnt(8)
	ds_write_b128 v158, v[60:63] offset:20480
	s_nop 0
	v_lshl_add_u64 v[4:5], v[132:133], 1, s[88:89]
	v_mov_b32_e32 v132, v166
	global_load_dwordx4 v[4:7], v[4:5], off
	s_nop 0
	v_lshl_add_u64 v[12:13], v[132:133], 1, s[18:19]
	v_add_u32_e32 v132, 0x4100, v162
	global_load_dwordx4 v[12:15], v[12:13], off
	s_nop 0
	v_lshl_add_u64 v[20:21], v[132:133], 1, s[88:89]
	v_add_u32_e32 v132, 0x2000, v166
	global_load_dwordx4 v[20:23], v[20:21], off
	s_nop 0
	v_lshl_add_u64 v[32:33], v[132:133], 1, s[18:19]
	v_add_u32_e32 v132, 0x8100, v162
	global_load_dwordx4 v[32:35], v[32:33], off
	s_nop 0
	v_lshl_add_u64 v[40:41], v[132:133], 1, s[88:89]
	v_add_u32_e32 v132, 0x4000, v166
	global_load_dwordx4 v[40:43], v[40:41], off
	s_nop 0
	v_lshl_add_u64 v[48:49], v[132:133], 1, s[18:19]
	v_add_u32_e32 v132, 0xc100, v162
	global_load_dwordx4 v[48:51], v[48:49], off
	s_nop 0
	v_lshl_add_u64 v[52:53], v[132:133], 1, s[88:89]
	v_add_u32_e32 v132, 0x6000, v166
	global_load_dwordx4 v[52:55], v[52:53], off
	s_nop 0
	v_lshl_add_u64 v[60:61], v[132:133], 1, s[18:19]
	global_load_dwordx4 v[60:63], v[60:61], off
	ds_read_b128 v[92:95], v134 offset:40960
	ds_read_b128 v[180:183], v134 offset:43520
	ds_read_b128 v[184:187], v135 offset:61440
	ds_read_b128 v[188:191], v135 offset:64000
	ds_read_b128 v[192:195], v134 offset:46080
	ds_read_b128 v[196:199], v134 offset:48640
	ds_read_b128 v[200:203], v160 offset:5120
	ds_read_b128 v[204:207], v160 offset:7680
	s_setprio 1
	s_waitcnt lgkmcnt(5)
	v_mfma_f32_16x16x32_bf16 v[96:99], v[184:187], v[92:95], v[96:99]
	v_mfma_f32_16x16x32_bf16 v[100:103], v[184:187], v[180:183], v[100:103]
	s_waitcnt lgkmcnt(3)
	v_mfma_f32_16x16x32_bf16 v[104:107], v[184:187], v[192:195], v[104:107]
	s_waitcnt lgkmcnt(2)
	v_mfma_f32_16x16x32_bf16 v[72:75], v[184:187], v[196:199], v[72:75]
	v_mfma_f32_16x16x32_bf16 v[112:115], v[188:191], v[180:183], v[112:115]
	v_mfma_f32_16x16x32_bf16 v[116:119], v[188:191], v[192:195], v[116:119]
	s_waitcnt lgkmcnt(0)
	v_mfma_f32_16x16x32_bf16 v[64:67], v[204:207], v[92:95], v[64:67]
	v_mfma_f32_16x16x32_bf16 v[80:83], v[204:207], v[192:195], v[80:83]
	v_mfma_f32_16x16x32_bf16 v[184:187], v[188:191], v[92:95], v[108:111]
	v_mfma_f32_16x16x32_bf16 v[188:191], v[188:191], v[196:199], v[76:79]
	v_mfma_f32_16x16x32_bf16 v[208:211], v[200:203], v[92:95], v[120:123]
	v_mfma_f32_16x16x32_bf16 v[212:215], v[200:203], v[180:183], v[124:127]
	v_mfma_f32_16x16x32_bf16 v[176:179], v[200:203], v[192:195], v[176:179]
	v_mfma_f32_16x16x32_bf16 v[200:203], v[200:203], v[196:199], v[88:91]
	v_mfma_f32_16x16x32_bf16 v[180:183], v[204:207], v[180:183], v[68:71]
	v_mfma_f32_16x16x32_bf16 v[192:195], v[204:207], v[196:199], v[84:87]
	s_setprio 0
	ds_read_b128 v[196:199], v134 offset:41024
	ds_read_b128 v[204:207], v134 offset:43584
	ds_read_b128 v[68:71], v135 offset:61504
	ds_read_b128 v[84:87], v135 offset:64064
	ds_read_b128 v[216:219], v134 offset:46144
	ds_read_b128 v[220:223], v134 offset:48704
	ds_read_b128 v[224:227], v161 offset:5120
	ds_read_b128 v[228:231], v161 offset:7680
	s_setprio 1
	s_waitcnt lgkmcnt(5)
	v_mfma_f32_16x16x32_bf16 v[124:127], v[68:71], v[196:199], v[96:99]
	v_mfma_f32_16x16x32_bf16 v[108:111], v[68:71], v[204:207], v[100:103]
	s_waitcnt lgkmcnt(3)
	v_mfma_f32_16x16x32_bf16 v[92:95], v[68:71], v[216:219], v[104:107]
	s_waitcnt lgkmcnt(2)
	v_mfma_f32_16x16x32_bf16 v[76:79], v[68:71], v[220:223], v[72:75]
	v_mfma_f32_16x16x32_bf16 v[120:123], v[84:87], v[196:199], v[184:187]
	v_mfma_f32_16x16x32_bf16 v[104:107], v[84:87], v[204:207], v[112:115]
	v_mfma_f32_16x16x32_bf16 v[88:91], v[84:87], v[216:219], v[116:119]
	v_mfma_f32_16x16x32_bf16 v[72:75], v[84:87], v[220:223], v[188:191]
	s_waitcnt lgkmcnt(1)
	v_mfma_f32_16x16x32_bf16 v[116:119], v[224:227], v[196:199], v[208:211]
	v_mfma_f32_16x16x32_bf16 v[100:103], v[224:227], v[204:207], v[212:215]
	v_mfma_f32_16x16x32_bf16 v[84:87], v[224:227], v[216:219], v[176:179]
	v_mfma_f32_16x16x32_bf16 v[68:71], v[224:227], v[220:223], v[200:203]
	s_waitcnt lgkmcnt(0)
	v_mfma_f32_16x16x32_bf16 v[112:115], v[228:231], v[196:199], v[64:67]
	v_mfma_f32_16x16x32_bf16 v[96:99], v[228:231], v[204:207], v[180:183]
	v_mfma_f32_16x16x32_bf16 v[80:83], v[228:231], v[216:219], v[80:83]
	v_mfma_f32_16x16x32_bf16 v[64:67], v[228:231], v[220:223], v[192:195]
	s_setprio 0
	v_add_u32_e32 v175, v150, v136
	v_add_u32_e32 v252, -1, v139
	v_add_u32_e32 v244, v138, v154
	v_add3_u32 v246, v138, v154, 16
	v_add3_u32 v248, v138, v154, 32
	v_add3_u32 v250, v138, v154, 48
	v_readlane_b32 s100, v237, 42
	v_readlane_b32 s101, v237, 43
	v_min_i32_e32 v244, v244, v252
	v_min_i32_e32 v246, v246, v252
	v_min_i32_e32 v248, v248, v252
	v_min_i32_e32 v250, v250, v252
	v_mov_b32_e32 v245, 0
	v_mov_b32_e32 v247, 0
	v_mov_b32_e32 v249, 0
	v_mov_b32_e32 v251, 0
	v_mov_b32_e32 v254, v130
	v_mov_b32_e32 v255, 0
	v_lshlrev_b64 v[254:255], 17, v[254:255]
	v_lshl_add_u64 v[254:255], s[100:101], 0, v[254:255]
	v_lshl_add_u64 v[244:245], v[244:245], 2, v[254:255]
	v_lshl_add_u64 v[246:247], v[246:247], 2, v[254:255]
	v_lshl_add_u64 v[248:249], v[248:249], 2, v[254:255]
	v_lshl_add_u64 v[250:251], v[250:251], 2, v[254:255]
	global_load_dword v240, v[244:245], off
	global_load_dword v241, v[246:247], off
	global_load_dword v242, v[248:249], off
	global_load_dword v243, v[250:251], off
	s_branch .LBB0_845

.LBB0_863:
	v_and_b32_e32 v131, 64, v131
	v_lshlrev_b32_e32 v134, 2, v159
	v_add_u32_e32 v136, v154, v138
	s_and_b32 s4, s16, 7
	v_cmp_lt_i32_e32 vcc, v136, v139
	v_lshlrev_b32_e32 v132, 1, v131
	v_lshlrev_b32_e32 v134, 1, v134
	s_and_saveexec_b64 s[0:1], vcc
	s_cbranch_execz .LBB0_865
	v_mov_b32_e32 v131, v133
	v_readlane_b32 s14, v237, 42
	v_lshlrev_b64 v[148:149], 17, v[130:131]
	v_readlane_b32 s15, v237, 43
	v_ashrrev_i32_e32 v137, 31, v136
	v_cvt_pk_bf16_f32 v112, v112, v113
	v_lshl_add_u64 v[148:149], s[14:15], 0, v[148:149]
	v_lshl_add_u64 v[136:137], v[136:137], 2, v[148:149]
	v_readlane_b32 s14, v237, 40
	v_cvt_pk_bf16_f32 v113, v114, v115
	v_readlane_b32 s15, v237, 41
	s_lshl_b32 s2, s4, 8
	v_mov_b32_e32 v135, v133
	v_cvt_pk_bf16_f32 v124, v124, v125
	v_cvt_pk_bf16_f32 v125, v126, v127
	v_cvt_pk_bf16_f32 v120, v120, v121
	v_cvt_pk_bf16_f32 v121, v122, v123
	v_cvt_pk_bf16_f32 v116, v116, v117
	v_cvt_pk_bf16_f32 v117, v118, v119
	s_waitcnt vmcnt(0)
	v_mov_b32_e32 v136, v240
	v_ashrrev_i32_e32 v137, 31, v136
	v_lshlrev_b64 v[114:115], 11, v[136:137]
	v_lshl_add_u64 v[114:115], s[14:15], 0, v[114:115]
	v_lshl_add_u64 v[114:115], v[114:115], 0, s[2:3]
	v_lshl_add_u64 v[114:115], v[114:115], 0, v[132:133]
	v_lshl_add_u64 v[114:115], v[114:115], 0, v[134:135]
	global_store_dwordx2 v[114:115], v[124:125], off
	global_store_dwordx2 v[114:115], v[120:121], off offset:32
	global_store_dwordx2 v[114:115], v[116:117], off offset:64
	global_store_dwordx2 v[114:115], v[112:113], off offset:96

.LBB0_1827:
	v_mul_lo_u32 v69, v134, s75
	v_bfe_u32 v69, v69, 10, 6
	v_mul_lo_u32 v70, v69, -6
	v_add_u32_e32 v70, v70, v134
	v_cmp_gt_i32_e32 vcc, 5, v70
	v_min_i32_e32 v77, 4, v70
	s_and_b32 s0, s61, 7
	v_cndmask_b32_e64 v71, 2, 1, vcc
	v_add_u32_e32 v76, 1, v70
	v_add_u32_e32 v77, -1, v77
	v_cmp_gt_i32_e32 vcc, 3, v70
	s_cmp_lt_u32 s0, 4
	v_lshlrev_b32_e32 v69, 2, v69
	v_cndmask_b32_e64 v70, v71, 0, vcc
	v_cndmask_b32_e32 v71, v77, v76, vcc
	s_cselect_b64 vcc, -1, 0
	s_lshl_b32 s0, s61, 7
	v_or_b32_e32 v70, v70, v69
	v_add_u32_e32 v69, v71, v69
	s_and_b32 s0, s0, 0x180
	s_waitcnt vmcnt(3)
	v_lshlrev_b32_e32 v135, 10, v65
	s_waitcnt vmcnt(2)
	v_lshlrev_b32_e32 v152, 10, v66
	v_cndmask_b32_e32 v65, v69, v70, vcc
	v_add_lshl_u32 v66, s0, v143, 10
	v_lshl_add_u32 v155, v65, 19, v66
	v_bfe_u32 v138, v64, 6, 1
	v_and_b32_e32 v65, 15, v64
	v_bfe_u32 v139, v64, 4, 2
	v_ashrrev_i32_e32 v64, 1, v64
	s_movk_i32 s0, 0xffc0
	v_and_or_b32 v156, v64, s0, v65
	v_lshlrev_b32_e32 v64, 4, v139
	v_lshl_or_b32 v65, v138, 6, v65
	s_movk_i32 s0, 0xa0
	v_mad_u64_u32 v[136:137], s[0:1], v156, s0, v[64:65]
	v_mul_u32_u24_e32 v65, 0x50, v65
	v_lshlrev_b32_e32 v66, 1, v133
	v_lshlrev_b32_e32 v65, 1, v65
	s_waitcnt vmcnt(1)
	v_lshlrev_b32_e32 v153, 10, v67
	s_waitcnt vmcnt(0)
	v_lshlrev_b32_e32 v154, 10, v68
	v_lshl_add_u32 v157, v75, 1, v66
	v_lshl_add_u32 v158, v72, 1, v66
	v_lshl_add_u32 v159, v73, 1, v66
	v_lshl_add_u32 v160, v74, 1, v66
	v_or_b32_e32 v66, 0x3c0, v133
	v_add_u32_e32 v137, v64, v65
	v_or_b32_e32 v67, 0xf000, v64
	v_add_u32_e32 v68, 0x1400, v65
	v_add_u32_e32 v65, 0x1e00, v65
	v_or_b32_e32 v64, 0xf040, v64
	v_add_u32_e32 v163, v64, v68
	v_add_u32_e32 v164, v64, v65
	v_add_u32_e32 v166, v66, v148
	v_mov_b32_e32 v64, 0
	s_mov_b32 s10, 0
	v_add_u32_e32 v161, v67, v68
	v_add_u32_e32 v162, v67, v65
	v_add_u32_e32 v165, v66, v147
	v_add_u32_e32 v167, v66, v146
	v_add_u32_e32 v168, 0x8000, v166
	v_add_u32_e32 v169, v66, v145
	v_add_u32_e32 v170, 0x10000, v166
	v_add_u32_e32 v171, v66, v144
	v_add_u32_e32 v172, 0x18000, v166
	v_mov_b32_e32 v173, v147
	v_mov_b32_e32 v174, v148
	v_mov_b32_e32 v175, v146
	v_mov_b32_e32 v176, v145
	v_mov_b32_e32 v177, v144
	v_mov_b32_e32 v178, v135
	v_mov_b32_e32 v179, v155
	v_mov_b32_e32 v180, v152
	v_mov_b32_e32 v181, v153
	v_mov_b32_e32 v182, v154
	v_mov_b32_e32 v65, v64
	v_mov_b32_e32 v66, v64
	v_mov_b32_e32 v67, v64
	v_mov_b32_e32 v80, v64
	v_mov_b32_e32 v81, v64
	v_mov_b32_e32 v82, v64
	v_mov_b32_e32 v83, v64
	v_mov_b32_e32 v96, v64
	v_mov_b32_e32 v97, v64
	v_mov_b32_e32 v98, v64
	v_mov_b32_e32 v99, v64
	v_mov_b32_e32 v112, v64
	v_mov_b32_e32 v113, v64
	v_mov_b32_e32 v114, v64
	v_mov_b32_e32 v115, v64
	v_mov_b32_e32 v68, v64
	v_mov_b32_e32 v69, v64
	v_mov_b32_e32 v70, v64
	v_mov_b32_e32 v71, v64
	v_mov_b32_e32 v84, v64
	v_mov_b32_e32 v85, v64
	v_mov_b32_e32 v86, v64
	v_mov_b32_e32 v87, v64
	v_mov_b32_e32 v100, v64
	v_mov_b32_e32 v101, v64
	v_mov_b32_e32 v102, v64
	v_mov_b32_e32 v103, v64
	v_mov_b32_e32 v116, v64
	v_mov_b32_e32 v117, v64
	v_mov_b32_e32 v118, v64
	v_mov_b32_e32 v119, v64
	v_mov_b32_e32 v72, v64
	v_mov_b32_e32 v73, v64
	v_mov_b32_e32 v74, v64
	v_mov_b32_e32 v75, v64
	v_mov_b32_e32 v88, v64
	v_mov_b32_e32 v89, v64
	v_mov_b32_e32 v90, v64
	v_mov_b32_e32 v91, v64
	v_mov_b32_e32 v104, v64
	v_mov_b32_e32 v105, v64
	v_mov_b32_e32 v106, v64
	v_mov_b32_e32 v107, v64
	v_mov_b32_e32 v120, v64
	v_mov_b32_e32 v121, v64
	v_mov_b32_e32 v122, v64
	v_mov_b32_e32 v123, v64
	v_mov_b32_e32 v76, v64
	v_mov_b32_e32 v77, v64
	v_mov_b32_e32 v78, v64
	v_mov_b32_e32 v79, v64
	v_mov_b32_e32 v92, v64
	v_mov_b32_e32 v93, v64
	v_mov_b32_e32 v94, v64
	v_mov_b32_e32 v95, v64
	v_mov_b32_e32 v108, v64
	v_mov_b32_e32 v109, v64
	v_mov_b32_e32 v110, v64
	v_mov_b32_e32 v111, v64
	v_mov_b32_e32 v124, v64
	v_mov_b32_e32 v125, v64
	v_mov_b32_e32 v126, v64
	v_mov_b32_e32 v127, v64
	v_add_u32_e32 v252, -1, v141
	v_add_u32_e32 v244, v140, v156
	v_add3_u32 v246, v140, v156, 16
	v_add3_u32 v248, v140, v156, 32
	v_add3_u32 v250, v140, v156, 48
	v_readlane_b32 s100, v237, 42
	v_readlane_b32 s101, v237, 43
	v_min_i32_e32 v244, v244, v252
	v_min_i32_e32 v246, v246, v252
	v_min_i32_e32 v248, v248, v252
	v_min_i32_e32 v250, v250, v252
	v_mov_b32_e32 v245, 0
	v_mov_b32_e32 v247, 0
	v_mov_b32_e32 v249, 0
	v_mov_b32_e32 v251, 0
	v_mov_b32_e32 v254, v132
	v_mov_b32_e32 v255, 0
	v_lshlrev_b64 v[254:255], 17, v[254:255]
	v_lshl_add_u64 v[254:255], s[100:101], 0, v[254:255]
	v_lshl_add_u64 v[244:245], v[244:245], 2, v[254:255]
	v_lshl_add_u64 v[246:247], v[246:247], 2, v[254:255]
	v_lshl_add_u64 v[248:249], v[248:249], 2, v[254:255]
	v_lshl_add_u64 v[250:251], v[250:251], 2, v[254:255]
	global_load_dword v240, v[244:245], off
	global_load_dword v241, v[246:247], off
	global_load_dword v242, v[248:249], off
	global_load_dword v243, v[250:251], off
	s_branch .LBB0_1829

.LBB0_1847:
	v_readlane_b32 s100, v237, 44
	v_readlane_b32 s101, v237, 45
	s_and_b32 s98, s60, 4
	s_mov_b32 s99, 0
	s_waitcnt vmcnt(0)
	v_mov_b32_e32 v244, v240
	v_mov_b32_e32 v245, 0
	v_mov_b32_e32 v246, v241
	v_mov_b32_e32 v247, 0
	v_mov_b32_e32 v248, v242
	v_mov_b32_e32 v249, 0
	v_mov_b32_e32 v250, v243
	v_mov_b32_e32 v251, 0
	v_lshl_add_u64 v[244:245], v[244:245], 3, s[100:101]
	v_lshl_add_u64 v[246:247], v[246:247], 3, s[100:101]
	v_lshl_add_u64 v[248:249], v[248:249], 3, s[100:101]
	v_lshl_add_u64 v[250:251], v[250:251], 3, s[100:101]
	v_lshl_add_u64 v[244:245], v[244:245], 0, s[98:99]
	v_lshl_add_u64 v[246:247], v[246:247], 0, s[98:99]
	v_lshl_add_u64 v[248:249], v[248:249], 0, s[98:99]
	v_lshl_add_u64 v[250:251], v[250:251], 0, s[98:99]
	global_load_dword v252, v[244:245], off
	global_load_dword v253, v[246:247], off
	global_load_dword v254, v[248:249], off
	global_load_dword v255, v[250:251], off
	s_lshl_b32 s0, s60, 1
	v_and_or_b32 v130, s0, 6, v138
	v_lshlrev_b32_e32 v130, 5, v130
	v_lshlrev_b32_e32 v133, 2, v139
	v_add_u32_e32 v138, v156, v140
	s_and_b32 s8, s60, 7
	v_cmp_lt_i32_e32 vcc, v138, v141
	v_lshlrev_b32_e32 v130, 1, v130
	v_lshlrev_b32_e32 v136, 1, v133
	s_and_saveexec_b64 s[0:1], vcc
	s_cbranch_execz .LBB0_1849
	v_mov_b32_e32 v133, v131
	v_readlane_b32 s10, v237, 42
	v_lshlrev_b64 v[158:159], 17, v[132:133]
	v_readlane_b32 s11, v237, 43
	v_ashrrev_i32_e32 v139, 31, v138
	s_and_b32 s94, s8, 4
	v_lshl_add_u64 v[158:159], s[10:11], 0, v[158:159]
	v_lshl_add_u64 v[158:159], v[138:139], 2, v[158:159]
	v_readlane_b32 s10, v237, 44
	v_readlane_b32 s11, v237, 45
	v_mul_f32_e32 v133, 0xbfb8aa3b, v124
	v_mul_f32_e32 v139, 0xbfb8aa3b, v125
	v_mul_f32_e32 v157, 0xbfb8aa3b, v126
	v_mul_f32_e32 v160, 0xbfb8aa3b, v120
	v_mul_f32_e32 v161, 0xbfb8aa3b, v121
	v_mul_f32_e32 v162, 0xbfb8aa3b, v122
	v_mul_f32_e32 v163, 0xbfb8aa3b, v123
	v_exp_f32_e32 v133, v133
	v_exp_f32_e32 v164, v139
	v_exp_f32_e32 v157, v157
	v_exp_f32_e32 v160, v160
	v_exp_f32_e32 v161, v161
	v_exp_f32_e32 v162, v162
	v_exp_f32_e32 v163, v163
	v_add_f32_e32 v133, 1.0, v133
	v_add_f32_e32 v164, 1.0, v164
	v_add_f32_e32 v157, 1.0, v157
	v_add_f32_e32 v165, 1.0, v160
	v_add_f32_e32 v166, 1.0, v161
	v_add_f32_e32 v167, 1.0, v162
	v_add_f32_e32 v168, 1.0, v163
	v_rcp_f32_e32 v160, v133
	v_rcp_f32_e32 v161, v164
	v_rcp_f32_e32 v162, v157
	v_rcp_f32_e32 v164, v165
	v_rcp_f32_e32 v165, v166
	v_add_u32_e32 v138, v138, v142
	v_rcp_f32_e32 v166, v167
	v_rcp_f32_e32 v167, v168
	v_ashrrev_i32_e32 v139, 31, v138
	s_lshl_b32 s9, s8, 7
	v_lshlrev_b64 v[138:139], 10, v[138:139]
	v_lshl_add_u64 v[138:139], s[88:89], 0, v[138:139]
	v_pk_mul_f32 v[124:125], v[124:125], v[160:161]
	v_pk_mul_f32 v[120:121], v[120:121], v[164:165]
	v_pk_mul_f32 v[122:123], v[122:123], v[166:167]
	v_pk_mul_f32 v[116:117], v[124:125], v[116:117]
	v_pk_mul_f32 v[112:113], v[120:121], v[112:113]
	v_mov_b32_e32 v137, v131
	v_pk_mul_f32 v[114:115], v[122:123], v[114:115]
	v_ashrrev_i32_e32 v159, 31, v158
	v_lshl_add_u64 v[158:159], v[158:159], 3, s[10:11]
	v_lshl_add_u64 v[158:159], v[158:159], 0, s[94:95]
	v_mul_f32_e32 v159, 0xbfb8aa3b, v127
	v_exp_f32_e32 v159, v159
	s_and_b32 s94, s9, 0x200
	v_lshl_add_u64 v[120:121], v[138:139], 0, s[94:95]
	v_lshl_add_u64 v[120:121], v[120:121], 0, v[130:131]
	v_add_f32_e32 v159, 1.0, v159
	v_rcp_f32_e32 v163, v159
	v_lshl_add_u64 v[120:121], v[120:121], 0, v[136:137]
	v_pk_mul_f32 v[126:127], v[126:127], v[162:163]
	s_nop 0
	v_pk_mul_f32 v[118:119], v[126:127], v[118:119]
	s_waitcnt vmcnt(0)
	v_mov_b32_e32 v158, v252
	v_pk_mul_f32 v[116:117], v[116:117], v[158:159] op_sel_hi:[1,0]
	v_pk_mul_f32 v[118:119], v[118:119], v[158:159] op_sel_hi:[1,0]
	v_pk_mul_f32 v[112:113], v[112:113], v[158:159] op_sel_hi:[1,0]
	v_pk_mul_f32 v[114:115], v[114:115], v[158:159] op_sel_hi:[1,0]
	v_cvt_pk_bf16_f32 v116, v116, v117
	v_cvt_pk_bf16_f32 v117, v118, v119
	v_cvt_pk_bf16_f32 v112, v112, v113
	v_cvt_pk_bf16_f32 v113, v114, v115
	global_store_dwordx2 v[120:121], v[116:117], off
	global_store_dwordx2 v[120:121], v[112:113], off offset:32

.LBB0_1967:
	v_lshlrev_b32_e32 v65, 1, v136
	v_lshl_add_u32 v155, v74, 1, v65
	v_lshl_add_u32 v156, v71, 1, v65
	v_lshl_add_u32 v157, v72, 1, v65
	v_lshl_add_u32 v158, v73, 1, v65
	v_or_b32_e32 v65, 0xc0, v136
	s_waitcnt lgkmcnt(0)
	s_barrier
	s_waitcnt vmcnt(15)
	ds_write_b128 v155, v[0:3] offset:40960
	s_waitcnt vmcnt(14)
	ds_write_b128 v155, v[8:11] offset:61440
	s_waitcnt vmcnt(13)
	ds_write_b128 v156, v[16:19] offset:40960
	s_waitcnt vmcnt(12)
	ds_write_b128 v156, v[24:27] offset:61440
	s_waitcnt vmcnt(11)
	ds_write_b128 v157, v[28:31] offset:40960
	s_waitcnt vmcnt(10)
	ds_write_b128 v157, v[36:39] offset:61440
	s_waitcnt vmcnt(9)
	ds_write_b128 v158, v[44:47] offset:40960
	s_waitcnt vmcnt(8)
	ds_write_b128 v158, v[56:59] offset:61440
	v_add_u32_e32 v44, v65, v142
	v_mov_b32_e32 v132, v44
	v_mul_lo_u32 v66, v146, s33
	v_lshl_add_u64 v[0:1], v[132:133], 1, s[88:89]
	v_add_u32_e32 v132, v65, v144
	global_load_dwordx4 v[0:3], v[0:1], off
	v_bfe_u32 v66, v66, 10, 6
	v_lshl_add_u64 v[8:9], v[132:133], 1, s[16:17]
	v_add_u32_e32 v132, 0x4000, v44
	global_load_dwordx4 v[8:11], v[8:9], off
	v_mul_lo_u32 v67, v66, -6
	v_lshl_add_u64 v[16:17], v[132:133], 1, s[88:89]
	v_add_u32_e32 v132, v65, v137
	global_load_dwordx4 v[16:19], v[16:17], off
	v_add_u32_e32 v151, v67, v146
	v_lshl_add_u64 v[24:25], v[132:133], 1, s[16:17]
	v_add_u32_e32 v132, 0x8000, v44
	global_load_dwordx4 v[24:27], v[24:25], off
	v_cmp_gt_i32_e32 vcc, 5, v151
	v_lshl_add_u64 v[28:29], v[132:133], 1, s[88:89]
	v_add_u32_e32 v132, v65, v148
	global_load_dwordx4 v[28:31], v[28:29], off
	v_cndmask_b32_e64 v67, 2, 1, vcc
	v_lshl_add_u64 v[36:37], v[132:133], 1, s[16:17]
	v_add_u32_e32 v132, 0xc000, v44
	global_load_dwordx4 v[36:39], v[36:37], off
	v_cmp_gt_i32_e64 s[8:9], 3, v151
	v_lshl_add_u64 v[44:45], v[132:133], 1, s[88:89]
	v_add_u32_e32 v132, v65, v149
	global_load_dwordx4 v[44:47], v[44:45], off
	v_cndmask_b32_e64 v152, v67, 0, s[8:9]
	v_lshl_add_u64 v[56:57], v[132:133], 1, s[16:17]
	global_load_dwordx4 v[56:59], v[56:57], off
	v_add_u32_e32 v64, v64, v145
	v_add_lshl_u32 v150, v64, v140, 9
	s_lshl_b32 s0, s92, 15
	v_lshlrev_b32_e32 v64, 20, v66
	v_lshlrev_b32_e32 v66, 18, v152
	s_and_b32 s0, s0, 0x38000
	v_or_b32_e32 v64, v66, v64
	v_or_b32_e32 v64, s0, v64
	v_add_u32_e32 v153, v64, v141
	v_and_b32_e32 v64, 15, v131
	v_bfe_u32 v159, v131, 4, 2
	v_ashrrev_i32_e32 v66, 1, v131
	s_movk_i32 s0, 0xffc0
	v_and_or_b32 v154, v66, s0, v64
	v_lshlrev_b32_e32 v64, 4, v159
	v_and_b32_e32 v66, 0x4f, v131
	s_movk_i32 s0, 0xa0
	v_mad_u64_u32 v[134:135], s[0:1], v154, s0, v[64:65]
	v_mul_u32_u24_e32 v66, 0x50, v66
	v_lshl_add_u32 v135, v66, 1, v64
	v_add_u32_e32 v64, v144, v143
	v_add_u32_e32 v164, v65, v64
	v_add_u32_e32 v166, v136, v64
	ds_read_b128 v[64:67], v134
	ds_read_b128 v[68:71], v134 offset:2560
	ds_read_b128 v[72:75], v135 offset:20480
	ds_read_b128 v[76:79], v135 offset:23040
	ds_read_b128 v[80:83], v134 offset:5120
	ds_read_b128 v[84:87], v134 offset:7680
	ds_read_b128 v[88:91], v135 offset:25600
	ds_read_b128 v[92:95], v135 offset:28160
	v_add_u32_e32 v162, v142, v136
	s_mov_b32 s12, 2
	s_mov_b32 s13, 0
	v_add_u32_e32 v160, 0xf000, v135
	v_add_u32_e32 v161, 0xf040, v135
	v_add_u32_e32 v163, 0x1c0, v162
	v_add_u32_e32 v165, 0x41c0, v162
	v_add_u32_e32 v167, 0x20c0, v166
	v_add_u32_e32 v168, 0x81c0, v162
	v_add_u32_e32 v169, 0x40c0, v166
	v_add_u32_e32 v170, 0xc1c0, v162
	v_add_u32_e32 v171, 0x60c0, v166
	v_add_u32_e32 v172, 0x2000, v153
	v_add_u32_e32 v173, 0x4000, v153
	v_add_u32_e32 v174, 0x6000, v153
	s_setprio 1
	s_waitcnt lgkmcnt(5)
	v_mfma_f32_16x16x32_bf16 v[96:99], v[72:75], v[64:67], 0
	v_mfma_f32_16x16x32_bf16 v[100:103], v[72:75], v[68:71], 0
	s_waitcnt lgkmcnt(3)
	v_mfma_f32_16x16x32_bf16 v[104:107], v[72:75], v[80:83], 0
	s_waitcnt lgkmcnt(2)
	v_mfma_f32_16x16x32_bf16 v[72:75], v[72:75], v[84:87], 0
	v_mfma_f32_16x16x32_bf16 v[108:111], v[76:79], v[64:67], 0
	v_mfma_f32_16x16x32_bf16 v[112:115], v[76:79], v[68:71], 0
	v_mfma_f32_16x16x32_bf16 v[116:119], v[76:79], v[80:83], 0
	v_mfma_f32_16x16x32_bf16 v[76:79], v[76:79], v[84:87], 0
	s_waitcnt lgkmcnt(1)
	v_mfma_f32_16x16x32_bf16 v[120:123], v[88:91], v[64:67], 0
	v_mfma_f32_16x16x32_bf16 v[124:127], v[88:91], v[68:71], 0
	v_mfma_f32_16x16x32_bf16 v[176:179], v[88:91], v[80:83], 0
	v_mfma_f32_16x16x32_bf16 v[88:91], v[88:91], v[84:87], 0
	s_waitcnt lgkmcnt(0)
	v_mfma_f32_16x16x32_bf16 v[64:67], v[92:95], v[64:67], 0
	v_mfma_f32_16x16x32_bf16 v[68:71], v[92:95], v[68:71], 0
	v_mfma_f32_16x16x32_bf16 v[80:83], v[92:95], v[80:83], 0
	v_mfma_f32_16x16x32_bf16 v[84:87], v[92:95], v[84:87], 0
	s_setprio 0
	ds_read_b128 v[92:95], v134 offset:64
	ds_read_b128 v[180:183], v134 offset:2624
	ds_read_b128 v[184:187], v135 offset:20544
	ds_read_b128 v[188:191], v135 offset:23104
	ds_read_b128 v[192:195], v134 offset:5184
	ds_read_b128 v[196:199], v134 offset:7744
	ds_read_b128 v[200:203], v135 offset:25664
	ds_read_b128 v[204:207], v135 offset:28224
	s_setprio 1
	s_waitcnt lgkmcnt(5)
	v_mfma_f32_16x16x32_bf16 v[96:99], v[184:187], v[92:95], v[96:99]
	v_mfma_f32_16x16x32_bf16 v[100:103], v[184:187], v[180:183], v[100:103]
	s_waitcnt lgkmcnt(3)
	v_mfma_f32_16x16x32_bf16 v[104:107], v[184:187], v[192:195], v[104:107]
	s_waitcnt lgkmcnt(2)
	v_mfma_f32_16x16x32_bf16 v[72:75], v[184:187], v[196:199], v[72:75]
	v_mfma_f32_16x16x32_bf16 v[108:111], v[188:191], v[92:95], v[108:111]
	v_mfma_f32_16x16x32_bf16 v[112:115], v[188:191], v[180:183], v[112:115]
	v_mfma_f32_16x16x32_bf16 v[116:119], v[188:191], v[192:195], v[116:119]
	v_mfma_f32_16x16x32_bf16 v[76:79], v[188:191], v[196:199], v[76:79]
	s_waitcnt lgkmcnt(1)
	v_mfma_f32_16x16x32_bf16 v[120:123], v[200:203], v[92:95], v[120:123]
	v_mfma_f32_16x16x32_bf16 v[124:127], v[200:203], v[180:183], v[124:127]
	v_mfma_f32_16x16x32_bf16 v[88:91], v[200:203], v[196:199], v[88:91]
	s_waitcnt lgkmcnt(0)
	v_mfma_f32_16x16x32_bf16 v[64:67], v[204:207], v[92:95], v[64:67]
	v_mfma_f32_16x16x32_bf16 v[68:71], v[204:207], v[180:183], v[68:71]
	v_mfma_f32_16x16x32_bf16 v[80:83], v[204:207], v[192:195], v[80:83]
	v_mfma_f32_16x16x32_bf16 v[84:87], v[204:207], v[196:199], v[84:87]
	v_mfma_f32_16x16x32_bf16 v[176:179], v[200:203], v[192:195], v[176:179]
	s_setprio 0
	v_add_u32_e32 v132, 0x100, v162
	s_barrier
	s_waitcnt vmcnt(15)
	ds_write_b128 v155, v[4:7]
	s_waitcnt vmcnt(14)
	ds_write_b128 v155, v[12:15] offset:20480
	s_waitcnt vmcnt(13)
	ds_write_b128 v156, v[20:23]
	s_waitcnt vmcnt(12)
	ds_write_b128 v156, v[32:35] offset:20480
	s_waitcnt vmcnt(11)
	ds_write_b128 v157, v[40:43]
	s_waitcnt vmcnt(10)
	ds_write_b128 v157, v[48:51] offset:20480
	s_waitcnt vmcnt(9)
	ds_write_b128 v158, v[52:55]
	s_waitcnt vmcnt(8)
	ds_write_b128 v158, v[60:63] offset:20480
	s_nop 0
	v_lshl_add_u64 v[4:5], v[132:133], 1, s[88:89]
	v_mov_b32_e32 v132, v166
	global_load_dwordx4 v[4:7], v[4:5], off
	s_nop 0
	v_lshl_add_u64 v[12:13], v[132:133], 1, s[16:17]
	v_add_u32_e32 v132, 0x4100, v162
	global_load_dwordx4 v[12:15], v[12:13], off
	s_nop 0
	v_lshl_add_u64 v[20:21], v[132:133], 1, s[88:89]
	v_add_u32_e32 v132, 0x2000, v166
	global_load_dwordx4 v[20:23], v[20:21], off
	s_nop 0
	v_lshl_add_u64 v[32:33], v[132:133], 1, s[16:17]
	v_add_u32_e32 v132, 0x8100, v162
	global_load_dwordx4 v[32:35], v[32:33], off
	s_nop 0
	v_lshl_add_u64 v[40:41], v[132:133], 1, s[88:89]
	v_add_u32_e32 v132, 0x4000, v166
	global_load_dwordx4 v[40:43], v[40:41], off
	s_nop 0
	v_lshl_add_u64 v[48:49], v[132:133], 1, s[16:17]
	v_add_u32_e32 v132, 0xc100, v162
	global_load_dwordx4 v[48:51], v[48:49], off
	s_nop 0
	v_lshl_add_u64 v[52:53], v[132:133], 1, s[88:89]
	v_add_u32_e32 v132, 0x6000, v166
	global_load_dwordx4 v[52:55], v[52:53], off
	s_nop 0
	v_lshl_add_u64 v[60:61], v[132:133], 1, s[16:17]
	global_load_dwordx4 v[60:63], v[60:61], off
	ds_read_b128 v[92:95], v134 offset:40960
	ds_read_b128 v[180:183], v134 offset:43520
	ds_read_b128 v[184:187], v135 offset:61440
	ds_read_b128 v[188:191], v135 offset:64000
	ds_read_b128 v[192:195], v134 offset:46080
	ds_read_b128 v[196:199], v134 offset:48640
	ds_read_b128 v[200:203], v160 offset:5120
	ds_read_b128 v[204:207], v160 offset:7680
	s_setprio 1
	s_waitcnt lgkmcnt(5)
	v_mfma_f32_16x16x32_bf16 v[96:99], v[184:187], v[92:95], v[96:99]
	v_mfma_f32_16x16x32_bf16 v[100:103], v[184:187], v[180:183], v[100:103]
	s_waitcnt lgkmcnt(3)
	v_mfma_f32_16x16x32_bf16 v[104:107], v[184:187], v[192:195], v[104:107]
	s_waitcnt lgkmcnt(2)
	v_mfma_f32_16x16x32_bf16 v[72:75], v[184:187], v[196:199], v[72:75]
	v_mfma_f32_16x16x32_bf16 v[112:115], v[188:191], v[180:183], v[112:115]
	v_mfma_f32_16x16x32_bf16 v[116:119], v[188:191], v[192:195], v[116:119]
	s_waitcnt lgkmcnt(0)
	v_mfma_f32_16x16x32_bf16 v[64:67], v[204:207], v[92:95], v[64:67]
	v_mfma_f32_16x16x32_bf16 v[80:83], v[204:207], v[192:195], v[80:83]
	v_mfma_f32_16x16x32_bf16 v[184:187], v[188:191], v[92:95], v[108:111]
	v_mfma_f32_16x16x32_bf16 v[188:191], v[188:191], v[196:199], v[76:79]
	v_mfma_f32_16x16x32_bf16 v[208:211], v[200:203], v[92:95], v[120:123]
	v_mfma_f32_16x16x32_bf16 v[212:215], v[200:203], v[180:183], v[124:127]
	v_mfma_f32_16x16x32_bf16 v[176:179], v[200:203], v[192:195], v[176:179]
	v_mfma_f32_16x16x32_bf16 v[200:203], v[200:203], v[196:199], v[88:91]
	v_mfma_f32_16x16x32_bf16 v[180:183], v[204:207], v[180:183], v[68:71]
	v_mfma_f32_16x16x32_bf16 v[192:195], v[204:207], v[196:199], v[84:87]
	s_setprio 0
	ds_read_b128 v[196:199], v134 offset:41024
	ds_read_b128 v[204:207], v134 offset:43584
	ds_read_b128 v[68:71], v135 offset:61504
	ds_read_b128 v[84:87], v135 offset:64064
	ds_read_b128 v[216:219], v134 offset:46144
	ds_read_b128 v[220:223], v134 offset:48704
	ds_read_b128 v[224:227], v161 offset:5120
	ds_read_b128 v[228:231], v161 offset:7680
	s_setprio 1
	s_waitcnt lgkmcnt(5)
	v_mfma_f32_16x16x32_bf16 v[124:127], v[68:71], v[196:199], v[96:99]
	v_mfma_f32_16x16x32_bf16 v[108:111], v[68:71], v[204:207], v[100:103]
	s_waitcnt lgkmcnt(3)
	v_mfma_f32_16x16x32_bf16 v[92:95], v[68:71], v[216:219], v[104:107]
	s_waitcnt lgkmcnt(2)
	v_mfma_f32_16x16x32_bf16 v[76:79], v[68:71], v[220:223], v[72:75]
	v_mfma_f32_16x16x32_bf16 v[120:123], v[84:87], v[196:199], v[184:187]
	v_mfma_f32_16x16x32_bf16 v[104:107], v[84:87], v[204:207], v[112:115]
	v_mfma_f32_16x16x32_bf16 v[88:91], v[84:87], v[216:219], v[116:119]
	v_mfma_f32_16x16x32_bf16 v[72:75], v[84:87], v[220:223], v[188:191]
	s_waitcnt lgkmcnt(1)
	v_mfma_f32_16x16x32_bf16 v[116:119], v[224:227], v[196:199], v[208:211]
	v_mfma_f32_16x16x32_bf16 v[100:103], v[224:227], v[204:207], v[212:215]
	v_mfma_f32_16x16x32_bf16 v[84:87], v[224:227], v[216:219], v[176:179]
	v_mfma_f32_16x16x32_bf16 v[68:71], v[224:227], v[220:223], v[200:203]
	s_waitcnt lgkmcnt(0)
	v_mfma_f32_16x16x32_bf16 v[112:115], v[228:231], v[196:199], v[64:67]
	v_mfma_f32_16x16x32_bf16 v[96:99], v[228:231], v[204:207], v[180:183]
	v_mfma_f32_16x16x32_bf16 v[80:83], v[228:231], v[216:219], v[80:83]
	v_mfma_f32_16x16x32_bf16 v[64:67], v[228:231], v[220:223], v[192:195]
	s_setprio 0
	v_add_u32_e32 v175, v150, v136
	v_add_u32_e32 v252, -1, v139
	v_add_u32_e32 v244, v138, v154
	v_add3_u32 v246, v138, v154, 16
	v_add3_u32 v248, v138, v154, 32
	v_add3_u32 v250, v138, v154, 48
	v_readlane_b32 s100, v237, 42
	v_readlane_b32 s101, v237, 43
	v_min_i32_e32 v244, v244, v252
	v_min_i32_e32 v246, v246, v252
	v_min_i32_e32 v248, v248, v252
	v_min_i32_e32 v250, v250, v252
	v_mov_b32_e32 v245, 0
	v_mov_b32_e32 v247, 0
	v_mov_b32_e32 v249, 0
	v_mov_b32_e32 v251, 0
	v_mov_b32_e32 v254, v130
	v_mov_b32_e32 v255, 0
	v_lshlrev_b64 v[254:255], 17, v[254:255]
	v_lshl_add_u64 v[254:255], s[100:101], 0, v[254:255]
	v_lshl_add_u64 v[244:245], v[244:245], 2, v[254:255]
	v_lshl_add_u64 v[246:247], v[246:247], 2, v[254:255]
	v_lshl_add_u64 v[248:249], v[248:249], 2, v[254:255]
	v_lshl_add_u64 v[250:251], v[250:251], 2, v[254:255]
	global_load_dword v240, v[244:245], off
	global_load_dword v241, v[246:247], off
	global_load_dword v242, v[248:249], off
	global_load_dword v243, v[250:251], off
	s_branch .LBB0_1969

.LBB0_1987:
	v_and_b32_e32 v131, 64, v131
	v_readlane_b32 s0, v237, 31
	v_lshlrev_b32_e32 v134, 2, v159
	v_add_u32_e32 v136, v154, v138
	v_readlane_b32 s1, v237, 32
	s_and_b32 s10, s0, 7
	v_cmp_lt_i32_e32 vcc, v136, v139
	v_lshlrev_b32_e32 v132, 1, v131
	v_lshlrev_b32_e32 v134, 1, v134
	s_and_saveexec_b64 s[0:1], vcc
	s_cbranch_execz .LBB0_1989
	v_mov_b32_e32 v131, v133
	v_readlane_b32 s12, v237, 42
	v_lshlrev_b64 v[148:149], 17, v[130:131]
	v_readlane_b32 s13, v237, 43
	v_ashrrev_i32_e32 v137, 31, v136
	v_cvt_pk_bf16_f32 v112, v112, v113
	v_lshl_add_u64 v[148:149], s[12:13], 0, v[148:149]
	v_lshl_add_u64 v[136:137], v[136:137], 2, v[148:149]
	v_readlane_b32 s12, v237, 40
	v_cvt_pk_bf16_f32 v113, v114, v115
	v_readlane_b32 s13, v237, 41
	s_lshl_b32 s92, s10, 8
	v_mov_b32_e32 v135, v133
	v_cvt_pk_bf16_f32 v124, v124, v125
	v_cvt_pk_bf16_f32 v125, v126, v127
	v_cvt_pk_bf16_f32 v120, v120, v121
	v_cvt_pk_bf16_f32 v121, v122, v123
	v_cvt_pk_bf16_f32 v116, v116, v117
	v_cvt_pk_bf16_f32 v117, v118, v119
	s_waitcnt vmcnt(0)
	v_mov_b32_e32 v136, v240
	v_ashrrev_i32_e32 v137, 31, v136
	v_lshlrev_b64 v[114:115], 11, v[136:137]
	v_lshl_add_u64 v[114:115], s[12:13], 0, v[114:115]
	v_lshl_add_u64 v[114:115], v[114:115], 0, s[92:93]
	v_lshl_add_u64 v[114:115], v[114:115], 0, v[132:133]
	v_lshl_add_u64 v[114:115], v[114:115], 0, v[134:135]
	global_store_dwordx2 v[114:115], v[124:125], off
	global_store_dwordx2 v[114:115], v[120:121], off offset:32
	global_store_dwordx2 v[114:115], v[116:117], off offset:64
	global_store_dwordx2 v[114:115], v[112:113], off offset:96
